# v25: v4 plus attention unit prologue waiting only for the K0 piece before its first barrier (waits to first consumer)
# speedup vs baseline: 1.0046x; 1.0046x over previous
.LBB0_1235:
	s_ashr_i32 s6, s34, 5
	s_lshr_b32 s0, s34, 1
	v_mov_b32_e32 v36, v208
	s_and_b32 s1, s34, 1
	s_and_b32 s0, s0, 14
	s_ashr_i32 s7, s6, 31
	v_readfirstlane_b32 s81, v36
	s_lshl_b32 s20, s77, 8
	s_or_b32 s52, s0, s1
	s_ashr_i32 s35, s81, 6
	s_lshl_b64 s[0:1], s[6:7], 13
	s_ashr_i32 s30, s20, 31
	s_add_u32 s0, s0, s20
	s_addc_u32 s1, s1, s30
	s_lshl_b32 s30, s35, 5
	s_ashr_i32 s31, s30, 31
	s_add_u32 s0, s0, s30
	s_addc_u32 s1, s1, s31
	s_lshl_b64 s[30:31], s[0:1], 11
	s_add_u32 s30, s38, s30
	s_addc_u32 s31, s39, s31
	s_lshl_b32 s36, s34, 6
	s_and_b32 s36, s36, 0x780
	s_add_u32 s30, s30, s36
	s_addc_u32 s31, s31, 0
	s_lshl_b64 s[6:7], s[6:7], 24
	s_add_u32 s37, s16, s6
	s_addc_u32 s44, s17, s7
	s_add_u32 s36, s37, s36
	s_addc_u32 s37, s44, 0
	s_add_u32 s6, s18, s6
	v_and_b32_e32 v211, 63, v36
	s_addc_u32 s7, s19, s7
	s_lshl_b32 s44, s52, 7
	s_add_u32 s6, s6, s44
	v_lshlrev_b32_e32 v0, 11, v211
	s_addc_u32 s7, s7, 0
	v_lshl_add_u64 v[2:3], s[36:37], 0, v[0:1]
	s_lshl_b32 s36, s35, 3
	s_ashr_i32 s37, s36, 31
	v_lshl_add_u64 v[196:197], s[36:37], 1, v[2:3]
	s_lshl_b32 s36, s35, 4
	v_bfe_u32 v0, v36, 2, 4
	v_and_or_b32 v0, s36, 48, v0
	v_lshlrev_b32_e32 v0, 11, v0
	v_lshl_add_u64 v[2:3], s[6:7], 0, v[0:1]
	s_ashr_i32 s6, s81, 3
	s_andn2_b32 s6, s6, 31
	s_ashr_i32 s7, s6, 31
	v_lshl_add_u64 v[2:3], s[6:7], 1, v[2:3]
	s_lshl_b32 s6, s35, 10
	v_lshlrev_b32_e32 v212, 3, v36
	s_cmp_lg_u32 0, -1
	v_and_b32_e32 v215, 24, v212
	s_cselect_b32 s7, 0, 0
	v_and_b32_e32 v213, 31, v36
	v_lshlrev_b32_e32 v0, 1, v215
	s_add_i32 s82, s6, s7
	s_mov_b32 s7, m0
	s_mov_b32 m0, s82
	s_nop 0
	global_load_lds_dwordx4 v[196:197], off
	s_mov_b32 m0, s7
	v_bfe_u32 v214, v36, 5, 1
	v_lshl_add_u64 v[34:35], v[2:3], 0, v[0:1]
	s_add_i32 s83, s82, 0x6000
	s_mov_b32 s7, m0
	s_mov_b32 m0, s83
	s_nop 0
	global_load_lds_dwordx4 v[34:35], off
	s_mov_b32 m0, s7
	v_lshlrev_b32_e32 v0, 11, v213
	v_lshl_add_u64 v[2:3], v[196:197], 0, s[22:23]
	s_add_i32 s7, s82, 0x2000
	s_mov_b32 s36, m0
	s_mov_b32 m0, s7
	s_nop 0
	global_load_lds_dwordx4 v[2:3], off
	s_mov_b32 m0, s36
	v_lshl_or_b32 v0, v214, 4, v0
	global_load_dwordx4 v[144:147], v0, s[30:31]
	global_load_dwordx4 v[136:139], v0, s[30:31] offset:32
	global_load_dwordx4 v[132:135], v0, s[30:31] offset:64
	global_load_dwordx4 v[128:131], v0, s[30:31] offset:96
	v_mov_b32_e32 v2, v1
	v_mov_b32_e32 v3, v1
	v_mov_b32_e32 v4, v1
	v_mov_b32_e32 v5, v1
	v_mov_b32_e32 v6, v1
	v_mov_b32_e32 v7, v1
	v_mov_b32_e32 v8, v1
	v_mov_b32_e32 v9, v1
	v_mov_b32_e32 v10, v1
	v_mov_b32_e32 v11, v1
	v_mov_b32_e32 v12, v1
	v_mov_b32_e32 v13, v1
	v_mov_b32_e32 v14, v1
	v_mov_b32_e32 v15, v1
	v_lshlrev_b32_e32 v0, 10, v214
	v_lshlrev_b32_e32 v16, 4, v213
	v_add3_u32 v220, 0, v0, v16
	v_mov_b32_e32 v0, v1
	v_mov_b64_e32 v[16:17], v[14:15]
	v_mov_b64_e32 v[14:15], v[12:13]
	v_mov_b64_e32 v[12:13], v[10:11]
	v_mov_b64_e32 v[10:11], v[8:9]
	v_mov_b64_e32 v[8:9], v[6:7]
	v_mov_b64_e32 v[6:7], v[4:5]
	v_mov_b64_e32 v[4:5], v[2:3]
	v_mov_b64_e32 v[2:3], v[0:1]
	v_lshl_add_u64 v[18:19], v[196:197], 0, s[24:25]
	s_add_i32 s7, s82, 0x4000
	s_mov_b32 s30, m0
	s_mov_b32 m0, s7
	s_nop 0
	global_load_lds_dwordx4 v[18:19], off
	s_mov_b32 m0, s30
	s_waitcnt vmcnt(7) lgkmcnt(0)
	s_barrier
	ds_read_b128 v[38:41], v220
	ds_read_b128 v[42:45], v220 offset:512
	s_addk_i32 s20, 0x100
	s_ashr_i32 s84, s20, 6
	s_cmp_gt_i32 s84, 4
	s_waitcnt vmcnt(3) lgkmcnt(1)
	v_mfma_f32_32x32x16_bf16 v[18:33], v[38:41], v[144:147], v[2:17]
	s_waitcnt lgkmcnt(0)
	v_mfma_f32_32x32x16_bf16 v[2:17], v[42:45], v[144:147], v[2:17]
	ds_read_b128 v[38:41], v220 offset:2048
	ds_read_b128 v[42:45], v220 offset:2560
	s_waitcnt vmcnt(2) lgkmcnt(1)
	v_mfma_f32_32x32x16_bf16 v[18:33], v[38:41], v[136:139], v[18:33]
	s_waitcnt lgkmcnt(0)
	v_mfma_f32_32x32x16_bf16 v[2:17], v[42:45], v[136:139], v[2:17]
	ds_read_b128 v[38:41], v220 offset:4096
	ds_read_b128 v[42:45], v220 offset:4608
	s_waitcnt vmcnt(1) lgkmcnt(1)
	v_mfma_f32_32x32x16_bf16 v[18:33], v[38:41], v[132:135], v[18:33]
	s_waitcnt lgkmcnt(0)
	v_mfma_f32_32x32x16_bf16 v[2:17], v[42:45], v[132:135], v[2:17]
	ds_read_b128 v[38:41], v220 offset:6144
	ds_read_b128 v[42:45], v220 offset:6656
	s_waitcnt vmcnt(0) lgkmcnt(1)
	v_mfma_f32_32x32x16_bf16 v[18:33], v[38:41], v[128:131], v[18:33]
	s_waitcnt lgkmcnt(0)
	v_mfma_f32_32x32x16_bf16 v[2:17], v[42:45], v[128:131], v[2:17]
	s_nop 15
	s_nop 7
	s_cbranch_scc1 .LBB0_1237
	s_sub_i32 s7, 4, s84
	s_ashr_i32 s20, s81, 7
	s_cmp_gt_i32 s7, s20
	s_cselect_b64 vcc, -1, 0
	s_nop 6
	v_cndmask_b32_e32 v17, v17, v210, vcc
	v_cndmask_b32_e32 v16, v16, v210, vcc
	v_cndmask_b32_e32 v15, v15, v210, vcc
	v_cndmask_b32_e32 v14, v14, v210, vcc
	v_cndmask_b32_e32 v13, v13, v210, vcc
	v_cndmask_b32_e32 v12, v12, v210, vcc
	v_cndmask_b32_e32 v11, v11, v210, vcc
	v_cndmask_b32_e32 v10, v10, v210, vcc
	v_cndmask_b32_e32 v9, v9, v210, vcc
	v_cndmask_b32_e32 v8, v8, v210, vcc
	v_cndmask_b32_e32 v7, v7, v210, vcc
	v_cndmask_b32_e32 v6, v6, v210, vcc
	v_cndmask_b32_e32 v5, v5, v210, vcc
	v_cndmask_b32_e32 v4, v4, v210, vcc
	v_cndmask_b32_e32 v3, v3, v210, vcc
	v_cndmask_b32_e32 v2, v2, v210, vcc
	v_cndmask_b32_e32 v33, v33, v210, vcc
	v_cndmask_b32_e32 v32, v32, v210, vcc
	v_cndmask_b32_e32 v31, v31, v210, vcc
	v_cndmask_b32_e32 v30, v30, v210, vcc
	v_cndmask_b32_e32 v29, v29, v210, vcc
	v_cndmask_b32_e32 v28, v28, v210, vcc
	v_cndmask_b32_e32 v27, v27, v210, vcc
	v_cndmask_b32_e32 v26, v26, v210, vcc
	v_cndmask_b32_e32 v25, v25, v210, vcc
	v_cndmask_b32_e32 v24, v24, v210, vcc
	v_cndmask_b32_e32 v23, v23, v210, vcc
	v_cndmask_b32_e32 v22, v22, v210, vcc
	v_cndmask_b32_e32 v21, v21, v210, vcc
	v_cndmask_b32_e32 v20, v20, v210, vcc
	v_cndmask_b32_e32 v19, v19, v210, vcc
	v_cndmask_b32_e32 v18, v18, v210, vcc
